# FoX steady loop: the step-head bias LDS read (read-wait-MFMA right after the barrier) is issued one step ahead into spare registers
# speedup vs baseline: 1.0091x; 1.0049x over previous
.LBB0_288:
	ds_read2_b32 v[246:247], v171 offset1:32
	s_waitcnt lgkmcnt(0)
.Lmy_fox_hA:
	s_mov_b32 s39, s38
	v_mov_b64_e32 v[68:69], s[38:39]
	v_mov_b64_e32 v[66:67], s[36:37]
	v_cndmask_b32_e64 v99, 0, v194, s[6:7]
	v_mov_b32_e32 v66, v246
	s_nop 1
	v_mfma_f32_32x32x16_bf16 v[82:97], v[66:69], v[98:101], 0
	v_mov_b64_e32 v[68:69], s[38:39]
	v_mov_b64_e32 v[66:67], s[36:37]
	v_mov_b32_e32 v66, v247
	s_nop 1
	v_mfma_f32_32x32x16_bf16 v[66:81], v[66:69], v[98:101], 0
	v_add_u32_e32 v99, s60, v193
	ds_read_b64_tr_b16 v[166:167], v99 offset:24576
	ds_read_b64_tr_b16 v[168:169], v99 offset:25088
	v_mfma_f32_32x32x16_bf16 v[82:97], v[162:165], v[114:117], v[82:97]
	v_add_f32_e32 v118, v48, v49
	v_add_f32_e32 v118, v50, v118
	v_add_f32_e32 v118, v51, v118
	v_add_f32_e32 v118, v52, v118
	v_add_f32_e32 v118, v53, v118
	v_cvt_pk_bf16_f32 v130, v48, v49
	v_cvt_pk_bf16_f32 v131, v50, v51
	ds_read_b64_tr_b16 v[48:49], v99 offset:28672
	ds_read_b64_tr_b16 v[50:51], v99 offset:29184
	v_mfma_f32_32x32x16_bf16 v[66:81], v[158:161], v[114:117], v[66:81]
	v_add_f32_e32 v118, v54, v118
	v_add_f32_e32 v118, v55, v118
	v_add_f32_e32 v118, v56, v118
	v_add_f32_e32 v118, v57, v118
	v_cvt_pk_bf16_f32 v132, v52, v53
	v_cvt_pk_bf16_f32 v133, v54, v55
	ds_read_b64_tr_b16 v[52:53], v99 offset:25600
	ds_read_b64_tr_b16 v[54:55], v99 offset:26112
	v_mfma_f32_32x32x16_bf16 v[82:97], v[154:157], v[110:113], v[82:97]
	v_add_f32_e32 v118, v58, v118
	v_add_f32_e32 v118, v59, v118
	v_add_f32_e32 v118, v60, v118
	v_add_f32_e32 v118, v61, v118
	v_cvt_pk_bf16_f32 v126, v56, v57
	v_cvt_pk_bf16_f32 v127, v58, v59
	ds_read_b64_tr_b16 v[56:57], v99 offset:29696
	ds_read_b64_tr_b16 v[58:59], v99 offset:30208
	v_mfma_f32_32x32x16_bf16 v[66:81], v[150:153], v[110:113], v[66:81]
	v_add_f32_e32 v118, v62, v118
	v_add_f32_e32 v118, v63, v118
	v_add_f32_e32 v118, v32, v118
	v_add_f32_e32 v118, v33, v118
	v_cvt_pk_bf16_f32 v128, v60, v61
	v_cvt_pk_bf16_f32 v129, v62, v63
	ds_read_b64_tr_b16 v[60:61], v99 offset:26624
	ds_read_b64_tr_b16 v[62:63], v99 offset:27136
	v_mfma_f32_32x32x16_bf16 v[82:97], v[146:149], v[106:109], v[82:97]
	v_add_f32_e32 v118, v34, v118
	v_add_f32_e32 v118, v35, v118
	v_add_f32_e32 v118, v36, v118
	v_add_f32_e32 v118, v37, v118
	v_cvt_pk_bf16_f32 v122, v32, v33
	v_cvt_pk_bf16_f32 v123, v34, v35
	ds_read_b64_tr_b16 v[32:33], v99 offset:30720
	ds_read_b64_tr_b16 v[34:35], v99 offset:31232
	v_mfma_f32_32x32x16_bf16 v[66:81], v[142:145], v[106:109], v[66:81]
	v_add_f32_e32 v118, v38, v118
	v_add_f32_e32 v118, v39, v118
	v_add_f32_e32 v118, v40, v118
	v_add_f32_e32 v118, v41, v118
	v_cvt_pk_bf16_f32 v124, v36, v37
	v_cvt_pk_bf16_f32 v125, v38, v39
	ds_read_b64_tr_b16 v[36:37], v99 offset:27648
	ds_read_b64_tr_b16 v[38:39], v99 offset:28160
	v_mfma_f32_32x32x16_bf16 v[82:97], v[138:141], v[102:105], v[82:97]
	v_add_f32_e32 v118, v42, v118
	v_add_f32_e32 v118, v43, v118
	v_add_f32_e32 v118, v44, v118
	v_add_f32_e32 v138, v45, v118
	v_cvt_pk_bf16_f32 v118, v40, v41
	v_cvt_pk_bf16_f32 v119, v42, v43
	ds_read_b64_tr_b16 v[40:41], v99 offset:31744
	ds_read_b64_tr_b16 v[42:43], v99 offset:32256
	v_mfma_f32_32x32x16_bf16 v[66:81], v[134:137], v[102:105], v[66:81]
	v_add_f32_e32 v99, v46, v138
	v_add_f32_e32 v99, v47, v99
	v_add_f32_e32 v99, 0, v99
	v_cvt_pk_bf16_f32 v120, v44, v45
	v_cvt_pk_bf16_f32 v121, v46, v47
	v_max_f32_e32 v44, v83, v83
	v_max_f32_e32 v45, v82, v82
	v_max_f32_e32 v44, v45, v44
	s_nop 3
	v_max3_f32 v45, v84, v85, v67
	v_max3_f32 v44, v44, v66, v68
	v_max3_f32 v44, v44, v69, v86
	v_max3_f32 v45, v45, v88, v89
	v_max3_f32 v44, v44, v87, v70
	v_max3_f32 v45, v45, v72, v73
	v_max3_f32 v44, v44, v71, v90
	v_max3_f32 v45, v45, v92, v93
	v_max3_f32 v44, v44, v91, v74
	v_max3_f32 v45, v45, v76, v77
	v_max3_f32 v44, v44, v75, v94
	v_max3_f32 v45, v45, v96, v97
	v_max3_f32 v44, v44, v95, v78
	v_max3_f32 v45, v45, v80, v81
	v_max3_f32 v44, v44, v79, v45
	v_mov_b32_e32 v45, v44
	s_add_u32 s60, s30, 0xfffe0000
	s_nop 0
	v_permlane32_swap_b32_e32 v44, v45
	s_addc_u32 s61, s31, -1
	s_add_i32 s1, s85, s89
	v_max_f32_e32 v45, v45, v45
	v_max_f32_e32 v44, v44, v44
	s_mov_b32 s33, m0
	s_mov_b32 m0, s1
	s_nop 0
	global_load_lds_dwordx4 v190, s[60:61]
	s_mov_b32 m0, s33
	s_add_u32 s60, s10, 0xfffe0000
	v_max_f32_e32 v44, v44, v45
	s_addc_u32 s61, s11, -1
	s_add_i32 s1, s55, s79
	s_mov_b32 s33, m0
	s_mov_b32 m0, s1
	s_nop 0
	global_load_lds_dwordx4 v191, s[60:61]
	s_mov_b32 m0, s33
	v_cmp_lt_f32_e32 vcc, s53, v44
	s_cmp_lg_u64 vcc, 0
	v_add_f32_e32 v64, v64, v99
	s_cselect_b64 s[60:61], -1, 0
	s_cbranch_vccnz .LBB0_296
.LBB0_289:
	s_waitcnt lgkmcnt(14)
	v_mfma_f32_32x32x16_bf16 v[0:15], v[130:133], v[166:169], v[0:15]
	v_exp_f32_e32 v82, v82
	v_exp_f32_e32 v83, v83
	v_exp_f32_e32 v84, v84
	v_exp_f32_e32 v85, v85
	s_waitcnt lgkmcnt(12)
	v_mfma_f32_32x32x16_bf16 v[16:31], v[130:133], v[48:51], v[16:31]
	v_exp_f32_e32 v86, v86
	v_exp_f32_e32 v87, v87
	v_exp_f32_e32 v88, v88
	v_exp_f32_e32 v89, v89
	v_add_u32_e32 v44, s55, v192
	ds_read_b128 v[166:169], v44
	ds_read_b128 v[162:165], v44 offset:512
	s_waitcnt lgkmcnt(12)
	v_mfma_f32_32x32x16_bf16 v[0:15], v[126:129], v[52:55], v[0:15]
	v_exp_f32_e32 v90, v90
	v_exp_f32_e32 v91, v91
	v_exp_f32_e32 v92, v92
	v_exp_f32_e32 v93, v93
	ds_read_b128 v[158:161], v44 offset:2048
	ds_read_b128 v[154:157], v44 offset:2560
	s_waitcnt lgkmcnt(12)
	v_mfma_f32_32x32x16_bf16 v[16:31], v[126:129], v[56:59], v[16:31]
	v_exp_f32_e32 v94, v94
	v_exp_f32_e32 v95, v95
	v_exp_f32_e32 v96, v96
	v_exp_f32_e32 v97, v97
	ds_read_b128 v[150:153], v44 offset:4096
	ds_read_b128 v[146:149], v44 offset:4608
	s_waitcnt lgkmcnt(12)
	v_mfma_f32_32x32x16_bf16 v[0:15], v[122:125], v[60:63], v[0:15]
	v_exp_f32_e32 v66, v66
	v_exp_f32_e32 v67, v67
	v_exp_f32_e32 v68, v68
	v_exp_f32_e32 v69, v69
	ds_read_b128 v[142:145], v44 offset:6144
	ds_read_b128 v[134:137], v44 offset:6656
	s_waitcnt lgkmcnt(12)
	v_mfma_f32_32x32x16_bf16 v[16:31], v[122:125], v[32:35], v[16:31]
	v_exp_f32_e32 v70, v70
	v_exp_f32_e32 v71, v71
	v_exp_f32_e32 v72, v72
	v_exp_f32_e32 v73, v73
	s_waitcnt lgkmcnt(10)
	v_mfma_f32_32x32x16_bf16 v[0:15], v[118:121], v[36:39], v[0:15]
	v_exp_f32_e32 v74, v74
	v_exp_f32_e32 v75, v75
	v_exp_f32_e32 v76, v76
	v_exp_f32_e32 v77, v77
	s_waitcnt lgkmcnt(8)
	v_mfma_f32_32x32x16_bf16 v[16:31], v[118:121], v[40:43], v[16:31]
	v_exp_f32_e32 v78, v78
	v_exp_f32_e32 v79, v79
	v_exp_f32_e32 v80, v80
	v_exp_f32_e32 v81, v81
	ds_read2_b32 v[244:245], v171 offset0:64 offset1:96
	s_waitcnt vmcnt(2) lgkmcnt(0)
	s_barrier
	s_andn2_b64 vcc, exec, s[60:61]
	v_add_u32_e32 v172, s41, v182
	s_cbranch_vccnz .LBB0_291
	s_waitcnt lgkmcnt(0)
	ds_read_b128 v[32:35], v172 offset:49248
	ds_read_b128 v[36:39], v172 offset:49216
	ds_read_b128 v[40:43], v172 offset:49184
	ds_read_b128 v[44:47], v172 offset:49152
	s_waitcnt lgkmcnt(3)
	v_pk_mul_f32 v[12:13], v[12:13], v[32:33]
	s_waitcnt lgkmcnt(2)
	v_pk_mul_f32 v[8:9], v[8:9], v[36:37]
	s_waitcnt lgkmcnt(1)
	v_pk_mul_f32 v[4:5], v[4:5], v[40:41]
	v_pk_mul_f32 v[14:15], v[14:15], v[34:35]
	v_pk_mul_f32 v[10:11], v[10:11], v[38:39]
	v_pk_mul_f32 v[6:7], v[6:7], v[42:43]
	s_waitcnt lgkmcnt(0)
	v_pk_mul_f32 v[2:3], v[2:3], v[46:47]
	v_pk_mul_f32 v[0:1], v[0:1], v[44:45]
	v_pk_mul_f32 v[28:29], v[28:29], v[32:33]
	v_pk_mul_f32 v[24:25], v[24:25], v[36:37]
	v_pk_mul_f32 v[20:21], v[20:21], v[40:41]
	v_pk_mul_f32 v[30:31], v[30:31], v[34:35]
	v_pk_mul_f32 v[26:27], v[26:27], v[38:39]
	v_pk_mul_f32 v[22:23], v[22:23], v[42:43]
	v_pk_mul_f32 v[18:19], v[18:19], v[46:47]
	v_pk_mul_f32 v[16:17], v[16:17], v[44:45]
.LBB0_291:
	s_add_i32 s1, s55, 0x2000
	s_cmpk_lg_i32 s55, 0x4000
	s_cselect_b32 s34, s1, 0
	s_mov_b32 s39, s38
	v_mov_b64_e32 v[32:33], s[36:37]
	v_mov_b64_e32 v[34:35], s[38:39]
	v_cndmask_b32_e64 v99, 0, v194, s[6:7]
	v_mov_b32_e32 v32, v244
	s_nop 1
	v_mfma_f32_32x32x16_bf16 v[48:63], v[32:35], v[98:101], 0
	v_mov_b64_e32 v[32:33], s[36:37]
	v_mov_b64_e32 v[34:35], s[38:39]
	v_mov_b32_e32 v32, v245
	s_nop 1
	v_mfma_f32_32x32x16_bf16 v[32:47], v[32:35], v[98:101], 0
	v_add_u32_e32 v99, s85, v193
	ds_read_b64_tr_b16 v[138:139], v99 offset:24576
	ds_read_b64_tr_b16 v[140:141], v99 offset:25088
	v_mfma_f32_32x32x16_bf16 v[48:63], v[166:169], v[114:117], v[48:63]
	v_add_f32_e32 v118, v82, v83
	v_add_f32_e32 v118, v84, v118
	v_add_f32_e32 v118, v85, v118
	v_add_f32_e32 v118, v86, v118
	v_add_f32_e32 v118, v87, v118
	v_cvt_pk_bf16_f32 v130, v82, v83
	v_cvt_pk_bf16_f32 v131, v84, v85
	ds_read_b64_tr_b16 v[82:83], v99 offset:28672
	ds_read_b64_tr_b16 v[84:85], v99 offset:29184
	v_mfma_f32_32x32x16_bf16 v[32:47], v[162:165], v[114:117], v[32:47]
	v_add_f32_e32 v118, v88, v118
	v_add_f32_e32 v118, v89, v118
	v_add_f32_e32 v118, v90, v118
	v_add_f32_e32 v118, v91, v118
	v_cvt_pk_bf16_f32 v132, v86, v87
	v_cvt_pk_bf16_f32 v133, v88, v89
	ds_read_b64_tr_b16 v[86:87], v99 offset:25600
	ds_read_b64_tr_b16 v[88:89], v99 offset:26112
	v_mfma_f32_32x32x16_bf16 v[48:63], v[158:161], v[110:113], v[48:63]
	v_add_f32_e32 v118, v92, v118
	v_add_f32_e32 v118, v93, v118
	v_add_f32_e32 v118, v94, v118
	v_add_f32_e32 v118, v95, v118
	v_cvt_pk_bf16_f32 v126, v90, v91
	v_cvt_pk_bf16_f32 v127, v92, v93
	ds_read_b64_tr_b16 v[90:91], v99 offset:29696
	ds_read_b64_tr_b16 v[92:93], v99 offset:30208
	v_mfma_f32_32x32x16_bf16 v[32:47], v[154:157], v[110:113], v[32:47]
	v_add_f32_e32 v118, v96, v118
	v_add_f32_e32 v118, v97, v118
	v_add_f32_e32 v118, v66, v118
	v_add_f32_e32 v118, v67, v118
	v_cvt_pk_bf16_f32 v128, v94, v95
	v_cvt_pk_bf16_f32 v129, v96, v97
	ds_read_b64_tr_b16 v[94:95], v99 offset:26624
	ds_read_b64_tr_b16 v[96:97], v99 offset:27136
	v_mfma_f32_32x32x16_bf16 v[48:63], v[150:153], v[106:109], v[48:63]
	v_add_f32_e32 v118, v68, v118
	v_add_f32_e32 v118, v69, v118
	v_add_f32_e32 v118, v70, v118
	v_add_f32_e32 v118, v71, v118
	v_cvt_pk_bf16_f32 v122, v66, v67
	v_cvt_pk_bf16_f32 v123, v68, v69
	ds_read_b64_tr_b16 v[66:67], v99 offset:30720
	ds_read_b64_tr_b16 v[68:69], v99 offset:31232
	v_mfma_f32_32x32x16_bf16 v[32:47], v[146:149], v[106:109], v[32:47]
	v_add_f32_e32 v118, v72, v118
	v_add_f32_e32 v118, v73, v118
	v_add_f32_e32 v118, v74, v118
	v_add_f32_e32 v118, v75, v118
	v_cvt_pk_bf16_f32 v124, v70, v71
	v_cvt_pk_bf16_f32 v125, v72, v73
	ds_read_b64_tr_b16 v[70:71], v99 offset:27648
	ds_read_b64_tr_b16 v[72:73], v99 offset:28160
	v_mfma_f32_32x32x16_bf16 v[48:63], v[142:145], v[102:105], v[48:63]
	v_add_f32_e32 v118, v76, v118
	v_add_f32_e32 v118, v77, v118
	v_add_f32_e32 v118, v78, v118
	v_add_f32_e32 v142, v79, v118
	v_cvt_pk_bf16_f32 v118, v74, v75
	v_cvt_pk_bf16_f32 v119, v76, v77
	ds_read_b64_tr_b16 v[74:75], v99 offset:31744
	ds_read_b64_tr_b16 v[76:77], v99 offset:32256
	v_mfma_f32_32x32x16_bf16 v[32:47], v[134:137], v[102:105], v[32:47]
	v_add_f32_e32 v99, v80, v142
	v_add_f32_e32 v99, v81, v99
	v_add_f32_e32 v99, 0, v99
	v_cvt_pk_bf16_f32 v120, v78, v79
	v_cvt_pk_bf16_f32 v121, v80, v81
	v_max_f32_e32 v78, v49, v49
	v_max_f32_e32 v79, v48, v48
	v_max_f32_e32 v78, v79, v78
	s_nop 3
	v_max3_f32 v79, v50, v51, v33
	v_max3_f32 v78, v78, v32, v34
	v_max3_f32 v78, v78, v35, v52
	v_max3_f32 v79, v79, v54, v55
	v_max3_f32 v78, v78, v53, v36
	v_max3_f32 v79, v79, v38, v39
	v_max3_f32 v78, v78, v37, v56
	v_max3_f32 v79, v79, v58, v59
	v_max3_f32 v78, v78, v57, v40
	v_max3_f32 v79, v79, v42, v43
	v_max3_f32 v78, v78, v41, v60
	v_max3_f32 v79, v79, v62, v63
	v_max3_f32 v78, v78, v61, v44
	v_max3_f32 v79, v79, v46, v47
	v_max3_f32 v78, v78, v45, v79
	v_mov_b32_e32 v79, v78
	s_nop 1
	v_permlane32_swap_b32_e32 v78, v79
	v_max_f32_e32 v79, v79, v79
	v_max_f32_e32 v78, v78, v78
	s_add_i32 s1, s55, s89
	s_mov_b32 s33, m0
	s_mov_b32 m0, s1
	s_nop 0
	global_load_lds_dwordx4 v190, s[30:31]
	s_mov_b32 m0, s33
	v_max_f32_e32 v78, v78, v79
	s_add_i32 s1, s34, s79
	s_mov_b32 s33, m0
	s_mov_b32 m0, s1
	s_nop 0
	global_load_lds_dwordx4 v191, s[10:11]
	s_mov_b32 m0, s33
	v_cmp_lt_f32_e32 vcc, s53, v78
	s_cmp_lg_u64 vcc, 0
	v_add_f32_e32 v64, v64, v99
	s_cselect_b64 s[60:61], -1, 0
	s_cbranch_vccnz .LBB0_299
.LBB0_292:
	s_waitcnt lgkmcnt(14)
	v_mfma_f32_32x32x16_bf16 v[0:15], v[130:133], v[138:141], v[0:15]
	v_exp_f32_e32 v48, v48
	v_exp_f32_e32 v49, v49
	v_exp_f32_e32 v50, v50
	v_exp_f32_e32 v51, v51
	s_waitcnt lgkmcnt(12)
	v_mfma_f32_32x32x16_bf16 v[16:31], v[130:133], v[82:85], v[16:31]
	v_exp_f32_e32 v52, v52
	v_exp_f32_e32 v53, v53
	v_exp_f32_e32 v54, v54
	v_exp_f32_e32 v55, v55
	v_add_u32_e32 v78, s34, v192
	ds_read_b128 v[162:165], v78
	ds_read_b128 v[158:161], v78 offset:512
	s_waitcnt lgkmcnt(12)
	v_mfma_f32_32x32x16_bf16 v[0:15], v[126:129], v[86:89], v[0:15]
	v_exp_f32_e32 v56, v56
	v_exp_f32_e32 v57, v57
	v_exp_f32_e32 v58, v58
	v_exp_f32_e32 v59, v59
	ds_read_b128 v[154:157], v78 offset:2048
	ds_read_b128 v[150:153], v78 offset:2560
	s_waitcnt lgkmcnt(12)
	v_mfma_f32_32x32x16_bf16 v[16:31], v[126:129], v[90:93], v[16:31]
	v_exp_f32_e32 v60, v60
	v_exp_f32_e32 v61, v61
	v_exp_f32_e32 v62, v62
	v_exp_f32_e32 v63, v63
	ds_read_b128 v[146:149], v78 offset:4096
	ds_read_b128 v[142:145], v78 offset:4608
	s_waitcnt lgkmcnt(12)
	v_mfma_f32_32x32x16_bf16 v[0:15], v[122:125], v[94:97], v[0:15]
	v_exp_f32_e32 v32, v32
	v_exp_f32_e32 v33, v33
	v_exp_f32_e32 v34, v34
	v_exp_f32_e32 v35, v35
	ds_read_b128 v[138:141], v78 offset:6144
	ds_read_b128 v[134:137], v78 offset:6656
	s_waitcnt lgkmcnt(12)
	v_mfma_f32_32x32x16_bf16 v[16:31], v[122:125], v[66:69], v[16:31]
	v_exp_f32_e32 v36, v36
	v_exp_f32_e32 v37, v37
	v_exp_f32_e32 v38, v38
	v_exp_f32_e32 v39, v39
	s_waitcnt lgkmcnt(10)
	v_mfma_f32_32x32x16_bf16 v[0:15], v[118:121], v[70:73], v[0:15]
	v_exp_f32_e32 v40, v40
	v_exp_f32_e32 v41, v41
	v_exp_f32_e32 v42, v42
	v_exp_f32_e32 v43, v43
	s_waitcnt lgkmcnt(8)
	v_mfma_f32_32x32x16_bf16 v[16:31], v[118:121], v[74:77], v[16:31]
	v_exp_f32_e32 v44, v44
	v_exp_f32_e32 v45, v45
	v_exp_f32_e32 v46, v46
	v_exp_f32_e32 v47, v47
	ds_read2_b32 v[246:247], v171 offset0:128 offset1:160
	s_waitcnt vmcnt(2) lgkmcnt(0)
	s_barrier
	s_andn2_b64 vcc, exec, s[60:61]
	s_cbranch_vccnz .LBB0_294
	s_waitcnt lgkmcnt(0)
	ds_read_b128 v[66:69], v172 offset:49248
	ds_read_b128 v[70:73], v172 offset:49216
	ds_read_b128 v[74:77], v172 offset:49184
	ds_read_b128 v[78:81], v172 offset:49152
	s_waitcnt lgkmcnt(3)
	v_pk_mul_f32 v[12:13], v[12:13], v[66:67]
	s_waitcnt lgkmcnt(2)
	v_pk_mul_f32 v[8:9], v[8:9], v[70:71]
	s_waitcnt lgkmcnt(1)
	v_pk_mul_f32 v[4:5], v[4:5], v[74:75]
	v_pk_mul_f32 v[14:15], v[14:15], v[68:69]
	v_pk_mul_f32 v[10:11], v[10:11], v[72:73]
	v_pk_mul_f32 v[6:7], v[6:7], v[76:77]
	s_waitcnt lgkmcnt(0)
	v_pk_mul_f32 v[2:3], v[2:3], v[80:81]
	v_pk_mul_f32 v[0:1], v[0:1], v[78:79]
	v_pk_mul_f32 v[28:29], v[28:29], v[66:67]
	v_pk_mul_f32 v[24:25], v[24:25], v[70:71]
	v_pk_mul_f32 v[20:21], v[20:21], v[74:75]
	v_pk_mul_f32 v[30:31], v[30:31], v[68:69]
	v_pk_mul_f32 v[26:27], v[26:27], v[72:73]
	v_pk_mul_f32 v[22:23], v[22:23], v[76:77]
	v_pk_mul_f32 v[18:19], v[18:19], v[80:81]
	v_pk_mul_f32 v[16:17], v[16:17], v[78:79]
